# static younger-half priority raised to level 3 instead of 1 (GEMM loops and GDN chain)
# speedup vs baseline: 1.0027x; 1.0027x over previous
; #define PG8_BAR __builtin_amdgcn_s_barrier()
; template <class Epi>
; __device__ __forceinline__ void gemm_phase(LAS unsigned char* lds, const Gemm g, const StaticOrder& S, const Epi& E) {
;     ...
;     if (wr == 1) PG8_BAR;
.LBB0_564:
	s_cmpk_gt_u32 s5, 0xff
	s_cbranch_scc0 .Lmy_prio_p2
	s_setprio 3

; #define LAS __attribute__((address_space(3)))
; __device__ __forceinline__ bf16_t f2bf(float f) { return (bf16_t)(pk2(f, f) & 0xFFFFu); }
; template <int MODE>
; __device__ NOINL void chain_item(const LAS Params* lp, int l, int item, bool ctx_out, LAS unsigned char* lds) {
;     ...
;         if (MODE == 0) {
;             *(LAS u32x4*)(TT + (tid >> 3) * 72 + (tid & 7) * 8) = rt;
;             if (tid < 192) gcs[tid] = rg;
;         } else {
;             const float ksc = __expf((float)(63 - pp) * lgl);
;             float kf[16]; unpack8(kk0, kf); unpack8(kk1, kf + 8);
; #pragma unroll
;             for (int e = 0; e < 16; ++e) KT[(lrow + e) * 72 + ppz] = f2bf(kf[e] * ksc);
;         }
;         __syncthreads();
;         if (n + 1 < 36) issue(n + 1);
.LBB0_1140:
	s_or_b64 exec, exec, s[46:47]
	v_readfirstlane_b32 s22, v30
	s_nop 3
	s_cmpk_gt_u32 s22, 0xff
	s_cbranch_scc0 .Lmy_prio_gdn
	s_setprio 3

; #define PG8_BAR __builtin_amdgcn_s_barrier()
; template <class Epi>
; __device__ __forceinline__ void gemm_phase(LAS unsigned char* lds, const Gemm g, const StaticOrder& S, const Epi& E) {
;     ...
;     if (wr == 1) PG8_BAR;
.LBB0_1482:
	s_cmpk_gt_u32 s3, 0xff
	s_cbranch_scc0 .Lmy_prio_p4
	s_setprio 3

; #define PG8_BAR __builtin_amdgcn_s_barrier()
; template <class Epi>
; __device__ __forceinline__ void gemm_phase(LAS unsigned char* lds, const Gemm g, const StaticOrder& S, const Epi& E) {
;     ...
;     if (wr == 1) PG8_BAR;
.LBB0_1847:
	s_cmpk_gt_u32 s28, 0xff
	s_cbranch_scc0 .Lmy_prio_p7
	s_setprio 3
